# attention inner loops: row-max merge across lane halves via v_permlane32_swap instead of ds_bpermute + lgkm wait (serial chain before the rescale test)
# speedup vs baseline: 1.0054x; 1.0024x over previous
; #define LAS __attribute__((address_space(3)))
; DI float fexp2(float x) { return __builtin_amdgcn_exp2f(x); }
; #define ATT_LOAD(t) do { _Pragma("unroll") for (int j = 0; j < 3; ++j) { const int id = tid + 512 * j; const int ch = id % 24; kreg[j] = *(const u32x4*)(ksrc[j] + (size_t)(t) * (ch < 16 ? kstep_n : kstep_p)); } \
;         _Pragma("unroll") for (int j = 0; j < 2; ++j) vreg[j] = *(const u32x4*)(vsrc[j] + (size_t)(t) * 8192); } while (0)
; DI void attn_item(LAS unsigned char* lds, int bh, int qb, const bf16_t* QH, const bf16_t* KN, const bf16_t* KPE, const bf16_t* VT, const bf16_t* P, bf16_t* MIX) {
;     ...
;     for (int t = 0; t < ntile; ++t) {
;         __syncthreads();
;         if (t + 1 < ntile) { ATT_STORE((t + 1) & 1); if (t + 2 < ntile) ATT_LOAD(t + 2); }
;         LAS unsigned char* kb = lds + (t & 1) * ATT_STAGE; LAS unsigned char* vb = kb + KBUF_B;
;         f32x16 S;
; #pragma unroll
;         for (int i = 0; i < 16; ++i) S[i] = 0.f;
;         { const LAS unsigned char* kp = kb + (kh * 32 + r) * KROW + 16 * h2;
;           __builtin_amdgcn_s_setprio(1);
; #pragma unroll
;           for (int ks = 0; ks < 12; ++ks) { const bf16x8 a = *(const LAS bf16x8*)(kp + 32 * ks); S = __builtin_amdgcn_mfma_f32_32x32x16_bf16(a, Qf[ks], S, 0, 0, 0); }
;           __builtin_amdgcn_sched_group_barrier(0x100, 4, 0);
; #pragma unroll
;           for (int i = 0; i < 8; ++i) { __builtin_amdgcn_sched_group_barrier(0x008, 1, 0); __builtin_amdgcn_sched_group_barrier(0x100, 1, 0); }
;           __builtin_amdgcn_sched_group_barrier(0x008, 4, 0);
;           __builtin_amdgcn_s_setprio(0); }
;         const bool diag = (t >= 2 * qb);
;         if (diag) {
;             const int key0 = t * 64 + kh * 32 + 4 * h2;
; #pragma unroll
;             for (int i = 0; i < 16; ++i) { const int key = key0 + (i & 3) + 8 * (i >> 2); if (key > qpos) S[i] = NEG; }
;         }
;         float mx = S[0];
; #pragma unroll
;         for (int i = 1; i < 16; ++i) mx = fmaxf(mx, S[i]);
;         mx = fmaxf(mx, __shfl_xor(mx, 32));
;         if (__any(mx > mrow + 8.f)) {
;             const float mnew = fmaxf(mrow, mx);
;             const float alpha = fexp2(mrow - mnew);
;             mrow = mnew; lrow *= alpha;
; #pragma unroll
;             for (int d = 0; d < 4; ++d)
; #pragma unroll
;                 for (int i = 0; i < 16; ++i) O[d][i] *= alpha;
;         }
.LBB0_594:
	s_bitcmp1_b32 s22, 0
	s_cselect_b32 s40, 0, 0xb400
	s_cselect_b32 s44, 0xb400, 0
	s_add_i32 s40, s40, 0
	v_add_u32_e32 v64, s40, v171
	s_waitcnt lgkmcnt(0)
	s_barrier
	s_waitcnt vmcnt(4)
	ds_write_b128 v64, v[128:131]
	v_add_u32_e32 v64, s40, v173
	s_waitcnt vmcnt(3)
	ds_write_b128 v64, v[132:135]
	v_add_u32_e32 v64, s40, v220
	s_waitcnt vmcnt(0)
	ds_write_b128 v64, v[144:147]
	v_add_u32_e32 v64, s40, v221
	ds_write_b128 v64, v[136:139] offset:25600
	v_add_u32_e32 v64, s40, v222
	ds_write_b128 v64, v[140:143] offset:25600
	v_lshlrev_b64 v[64:65], v168, s[22:23]
	v_lshl_add_u64 v[64:65], v[64:65], 1, v[190:191]
	global_load_dwordx4 v[128:131], v[64:65], off
	v_lshlrev_b64 v[64:65], v170, s[22:23]
	v_lshl_add_u64 v[64:65], v[64:65], 1, v[192:193]
	global_load_dwordx4 v[132:135], v[64:65], off
	v_lshlrev_b64 v[64:65], v172, s[22:23]
	v_lshl_add_u64 v[64:65], v[64:65], 1, v[194:195]
	global_load_dwordx4 v[144:147], v[64:65], off
	global_load_dwordx4 v[136:139], v[218:219], off
	global_load_dwordx4 v[140:143], v[216:217], off
	s_add_i32 s44, s44, 0
	v_add3_u32 v235, s44, v233, v164
	s_setprio 1
	ds_read_b128 v[64:67], v235
	ds_read_b128 v[240:243], v235 offset:32
	ds_read_b128 v[244:247], v235 offset:64
	ds_read_b128 v[248:251], v235 offset:96
	s_waitcnt lgkmcnt(3)
	v_mfma_f32_32x32x16_bf16 v[64:79], v[64:67], v[124:127], 0
	ds_read_b128 v[236:239], v235 offset:128
	s_waitcnt lgkmcnt(3)
	v_mfma_f32_32x32x16_bf16 v[64:79], v[240:243], v[120:123], v[64:79]
	ds_read_b128 v[240:243], v235 offset:160
	s_waitcnt lgkmcnt(3)
	v_mfma_f32_32x32x16_bf16 v[64:79], v[244:247], v[116:119], v[64:79]
	ds_read_b128 v[244:247], v235 offset:192
	s_waitcnt lgkmcnt(3)
	v_mfma_f32_32x32x16_bf16 v[64:79], v[248:251], v[112:115], v[64:79]
	ds_read_b128 v[248:251], v235 offset:224
	s_waitcnt lgkmcnt(3)
	v_mfma_f32_32x32x16_bf16 v[64:79], v[236:239], v[108:111], v[64:79]
	ds_read_b128 v[236:239], v235 offset:256
	s_waitcnt lgkmcnt(3)
	v_mfma_f32_32x32x16_bf16 v[64:79], v[240:243], v[104:107], v[64:79]
	ds_read_b128 v[240:243], v235 offset:288
	s_waitcnt lgkmcnt(3)
	v_mfma_f32_32x32x16_bf16 v[64:79], v[244:247], v[100:103], v[64:79]
	ds_read_b128 v[244:247], v235 offset:320
	s_waitcnt lgkmcnt(3)
	v_mfma_f32_32x32x16_bf16 v[64:79], v[248:251], v[96:99], v[64:79]
	ds_read_b128 v[248:251], v235 offset:352
	s_waitcnt lgkmcnt(3)
	v_mfma_f32_32x32x16_bf16 v[64:79], v[236:239], v[84:87], v[64:79]
	s_waitcnt lgkmcnt(2)
	v_mfma_f32_32x32x16_bf16 v[64:79], v[240:243], v[88:91], v[64:79]
	s_waitcnt lgkmcnt(1)
	v_mfma_f32_32x32x16_bf16 v[64:79], v[244:247], v[92:95], v[64:79]
	s_waitcnt lgkmcnt(0)
	v_mfma_f32_32x32x16_bf16 v[64:79], v[248:251], v[80:83], v[64:79]
	s_setprio 0
	s_nop 10
	v_max_f32_e32 v235, v65, v65
	v_max_f32_e32 v236, v64, v64
	v_max_f32_e32 v235, v236, v235
	v_max3_f32 v235, v235, v66, v67
	v_max3_f32 v235, v235, v68, v69
	v_max3_f32 v235, v235, v70, v71
	v_max3_f32 v235, v235, v72, v73
	v_max3_f32 v235, v235, v74, v75
	v_max3_f32 v235, v235, v76, v77
	v_max3_f32 v235, v235, v78, v79
	v_mov_b32_e32 v236, v235
	s_nop 1
	v_permlane32_swap_b32_e32 v236, v235
	s_waitcnt lgkmcnt(0)
	v_max_f32_e32 v236, v236, v236
	v_max_f32_e32 v235, v235, v236
	v_add_f32_e32 v236, 0x41000000, v214
	v_cmp_gt_f32_e32 vcc, v235, v236
	s_cbranch_vccz .LBB0_593
	v_max_f32_e32 v235, v235, v235
	v_max_f32_e32 v236, v214, v214
	v_max_f32_e32 v235, v236, v235
	v_sub_f32_e32 v214, v214, v235
	v_exp_f32_e32 v214, v214
	s_nop 0
	v_pk_mul_f32 v[62:63], v[62:63], v[214:215] op_sel_hi:[1,0]
	v_pk_mul_f32 v[60:61], v[60:61], v[214:215] op_sel_hi:[1,0]
	v_pk_mul_f32 v[58:59], v[58:59], v[214:215] op_sel_hi:[1,0]
	v_pk_mul_f32 v[56:57], v[56:57], v[214:215] op_sel_hi:[1,0]
	v_pk_mul_f32 v[54:55], v[54:55], v[214:215] op_sel_hi:[1,0]
	v_pk_mul_f32 v[52:53], v[52:53], v[214:215] op_sel_hi:[1,0]
	v_pk_mul_f32 v[50:51], v[50:51], v[214:215] op_sel_hi:[1,0]
	v_pk_mul_f32 v[48:49], v[48:49], v[214:215] op_sel_hi:[1,0]
	v_pk_mul_f32 v[46:47], v[46:47], v[214:215] op_sel_hi:[1,0]
	v_pk_mul_f32 v[44:45], v[44:45], v[214:215] op_sel_hi:[1,0]
	v_pk_mul_f32 v[42:43], v[42:43], v[214:215] op_sel_hi:[1,0]
	v_pk_mul_f32 v[40:41], v[40:41], v[214:215] op_sel_hi:[1,0]
	v_pk_mul_f32 v[38:39], v[38:39], v[214:215] op_sel_hi:[1,0]
	v_pk_mul_f32 v[36:37], v[36:37], v[214:215] op_sel_hi:[1,0]
	v_pk_mul_f32 v[34:35], v[34:35], v[214:215] op_sel_hi:[1,0]
	v_pk_mul_f32 v[32:33], v[32:33], v[214:215] op_sel_hi:[1,0]
	v_pk_mul_f32 v[30:31], v[30:31], v[214:215] op_sel_hi:[1,0]
	v_pk_mul_f32 v[28:29], v[28:29], v[214:215] op_sel_hi:[1,0]
	v_pk_mul_f32 v[26:27], v[26:27], v[214:215] op_sel_hi:[1,0]
	v_pk_mul_f32 v[24:25], v[24:25], v[214:215] op_sel_hi:[1,0]
	v_pk_mul_f32 v[22:23], v[22:23], v[214:215] op_sel_hi:[1,0]
	v_pk_mul_f32 v[20:21], v[20:21], v[214:215] op_sel_hi:[1,0]
	v_pk_mul_f32 v[18:19], v[18:19], v[214:215] op_sel_hi:[1,0]
	v_pk_mul_f32 v[16:17], v[16:17], v[214:215] op_sel_hi:[1,0]
	v_pk_mul_f32 v[14:15], v[14:15], v[214:215] op_sel_hi:[1,0]
	v_pk_mul_f32 v[12:13], v[12:13], v[214:215] op_sel_hi:[1,0]
	v_pk_mul_f32 v[10:11], v[10:11], v[214:215] op_sel_hi:[1,0]
	v_pk_mul_f32 v[8:9], v[8:9], v[214:215] op_sel_hi:[1,0]
	v_pk_mul_f32 v[6:7], v[6:7], v[214:215] op_sel_hi:[1,0]
	v_pk_mul_f32 v[4:5], v[4:5], v[214:215] op_sel_hi:[1,0]
	v_pk_mul_f32 v[2:3], v[2:3], v[214:215] op_sel_hi:[1,0]
	v_pk_mul_f32 v[0:1], v[0:1], v[214:215] op_sel_hi:[1,0]
	v_mul_f32_e32 v234, v234, v214
	v_mov_b32_e32 v214, v235
	s_branch .LBB0_593

; DI float fexp2(float x) { return __builtin_amdgcn_exp2f(x); }
; DI void attn_item(LAS unsigned char* lds, int bh, int qb, const bf16_t* QH, const bf16_t* KN, const bf16_t* KPE, const bf16_t* VT, const bf16_t* P, bf16_t* MIX) {
;     ...
;         float mx = S[0];
; #pragma unroll
;         for (int i = 1; i < 16; ++i) mx = fmaxf(mx, S[i]);
;         mx = fmaxf(mx, __shfl_xor(mx, 32));
;         if (__any(mx > mrow + 8.f)) {
;             const float mnew = fmaxf(mrow, mx);
;             const float alpha = fexp2(mrow - mnew);
;             mrow = mnew; lrow *= alpha;
; #pragma unroll
;             for (int d = 0; d < 4; ++d)
; #pragma unroll
;                 for (int i = 0; i < 16; ++i) O[d][i] *= alpha;
;         }
.LBB0_614:
	s_nop 6
	v_max_f32_e32 v185, v65, v65
	v_max_f32_e32 v187, v64, v64
	v_max_f32_e32 v185, v187, v185
	v_max3_f32 v185, v185, v66, v67
	v_max3_f32 v185, v185, v68, v69
	v_max3_f32 v185, v185, v70, v71
	v_max3_f32 v185, v185, v72, v73
	v_max3_f32 v185, v185, v74, v75
	v_max3_f32 v185, v185, v76, v77
	v_max3_f32 v185, v185, v78, v79
	v_mov_b32_e32 v187, v185
	s_nop 1
	v_permlane32_swap_b32_e32 v187, v185
	s_waitcnt lgkmcnt(0)
	v_max_f32_e32 v187, v187, v187
	v_max_f32_e32 v185, v185, v187
	v_add_f32_e32 v187, 0x41000000, v200
	v_cmp_gt_f32_e32 vcc, v185, v187
	s_cbranch_vccz .Lsel609
	v_max_f32_e32 v185, v185, v185
	v_max_f32_e32 v187, v200, v200
	v_max_f32_e32 v185, v187, v185
	v_sub_f32_e32 v187, v200, v185
	v_exp_f32_e32 v200, v187
	s_nop 0
	v_pk_mul_f32 v[62:63], v[62:63], v[200:201] op_sel_hi:[1,0]
	v_pk_mul_f32 v[60:61], v[60:61], v[200:201] op_sel_hi:[1,0]
	v_pk_mul_f32 v[58:59], v[58:59], v[200:201] op_sel_hi:[1,0]
	v_pk_mul_f32 v[56:57], v[56:57], v[200:201] op_sel_hi:[1,0]
	v_pk_mul_f32 v[54:55], v[54:55], v[200:201] op_sel_hi:[1,0]
	v_pk_mul_f32 v[52:53], v[52:53], v[200:201] op_sel_hi:[1,0]
	v_pk_mul_f32 v[50:51], v[50:51], v[200:201] op_sel_hi:[1,0]
	v_pk_mul_f32 v[48:49], v[48:49], v[200:201] op_sel_hi:[1,0]
	v_pk_mul_f32 v[46:47], v[46:47], v[200:201] op_sel_hi:[1,0]
	v_pk_mul_f32 v[44:45], v[44:45], v[200:201] op_sel_hi:[1,0]
	v_pk_mul_f32 v[42:43], v[42:43], v[200:201] op_sel_hi:[1,0]
	v_pk_mul_f32 v[40:41], v[40:41], v[200:201] op_sel_hi:[1,0]
	v_pk_mul_f32 v[38:39], v[38:39], v[200:201] op_sel_hi:[1,0]
	v_pk_mul_f32 v[36:37], v[36:37], v[200:201] op_sel_hi:[1,0]
	v_pk_mul_f32 v[34:35], v[34:35], v[200:201] op_sel_hi:[1,0]
	v_pk_mul_f32 v[32:33], v[32:33], v[200:201] op_sel_hi:[1,0]
	v_pk_mul_f32 v[30:31], v[30:31], v[200:201] op_sel_hi:[1,0]
	v_pk_mul_f32 v[28:29], v[28:29], v[200:201] op_sel_hi:[1,0]
	v_pk_mul_f32 v[26:27], v[26:27], v[200:201] op_sel_hi:[1,0]
	v_pk_mul_f32 v[24:25], v[24:25], v[200:201] op_sel_hi:[1,0]
	v_pk_mul_f32 v[22:23], v[22:23], v[200:201] op_sel_hi:[1,0]
	v_pk_mul_f32 v[20:21], v[20:21], v[200:201] op_sel_hi:[1,0]
	v_pk_mul_f32 v[18:19], v[18:19], v[200:201] op_sel_hi:[1,0]
	v_pk_mul_f32 v[16:17], v[16:17], v[200:201] op_sel_hi:[1,0]
	v_pk_mul_f32 v[14:15], v[14:15], v[200:201] op_sel_hi:[1,0]
	v_pk_mul_f32 v[12:13], v[12:13], v[200:201] op_sel_hi:[1,0]
	v_pk_mul_f32 v[10:11], v[10:11], v[200:201] op_sel_hi:[1,0]
	v_pk_mul_f32 v[8:9], v[8:9], v[200:201] op_sel_hi:[1,0]
	v_pk_mul_f32 v[6:7], v[6:7], v[200:201] op_sel_hi:[1,0]
	v_pk_mul_f32 v[4:5], v[4:5], v[200:201] op_sel_hi:[1,0]
	v_pk_mul_f32 v[2:3], v[2:3], v[200:201] op_sel_hi:[1,0]
	v_pk_mul_f32 v[0:1], v[0:1], v[200:201] op_sel_hi:[1,0]
	v_mul_f32_e32 v183, v183, v200
	v_mov_b32_e32 v200, v185
	s_branch .Lsel609
